# post-prep grid-wide sync replaced by a producer/consumer flag (the 96 modulation items count up, every workgroup waits only for that count) so late-launching workgroups no longer hold back the first n
# speedup vs baseline: 1.0108x; 1.0027x over previous
.Lmd_done:
	s_waitcnt vmcnt(0)
	s_barrier
	v_cmp_eq_u32_e32 vcc, 0, v143
	s_and_saveexec_b64 s[24:25], vcc
	s_cbranch_execz .Lmd_sig
	buffer_wbl2 sc1
	s_waitcnt vmcnt(0)
	s_add_u32 s10, s50, 0x1aa5d080
	s_addc_u32 s11, s51, 0
	v_mov_b32_e32 v2, 0
	v_mov_b32_e32 v3, 1
	global_atomic_add v2, v3, s[10:11]
	s_waitcnt vmcnt(0)
.Lmd_sig:
	s_or_b64 exec, exec, s[24:25]
	s_branch .LBB0_14

.LBB0_20:
	s_or_b64 exec, exec, s[4:5]
	s_load_dwordx16 s[56:71], s[0:1], 0x40
	v_lshrrev_b32_e32 v2, 20, v0
	v_lshrrev_b32_e32 v0, 10, v0
	v_or_b32_e32 v0, v0, v2
	s_movk_i32 s0, 0x3ff
	s_waitcnt lgkmcnt(0)
	v_writelane_b32 v253, s56, 18
	v_and_or_b32 v0, v0, s0, v57
	v_cmp_eq_u32_e32 vcc, 0, v0
	v_writelane_b32 v253, s57, 19
	v_writelane_b32 v253, s58, 20
	v_writelane_b32 v253, s59, 21
	v_writelane_b32 v253, s60, 22
	v_writelane_b32 v253, s61, 23
	v_writelane_b32 v253, s62, 24
	v_writelane_b32 v253, s63, 25
	v_writelane_b32 v253, s64, 26
	v_writelane_b32 v253, s65, 27
	v_writelane_b32 v253, s66, 28
	v_writelane_b32 v253, s67, 29
	v_writelane_b32 v253, s68, 30
	v_writelane_b32 v253, s69, 31
	v_writelane_b32 v253, s70, 32
	v_writelane_b32 v253, s71, 33
	s_barrier
	s_and_saveexec_b64 s[0:1], vcc
	s_cbranch_execz .LBB0_30
	s_add_u32 s10, s50, 0x1aa5d080
	s_addc_u32 s11, s51, 0
	v_mov_b32_e32 v0, 0
.Lmr_spin:
	global_load_dword v3, v0, s[10:11] sc1
	s_waitcnt vmcnt(0)
	v_cmp_gt_u32_e32 vcc, 0x60, v3
	s_cbranch_vccz .Lmr_ready
	s_sleep 1
	s_branch .Lmr_spin
.Lmr_ready:
	buffer_inv sc1
	s_waitcnt vmcnt(0)
